# final normalisation scale with packed f32 multiplies (same operation order, half the VALU instructions)
# baseline (speedup 1.0000x reference)
; __device__ __forceinline__ void final_phase(const Params& p) {
;     ...
;     s = wsum64(s);
;     const float rs = rsqrtf(s * (1.0f / 1024.0f) + 1e-6f);
;     float* xr = p.out + (size_t)row * 1024;
; #pragma unroll
;     for (int i = 0; i < 4; i++) {
;       float4 v = *(float4*)(xr + i * 256 + lane * 4);
;       float4 gg = *(const float4*)(g + i * 256 + lane * 4);
;       v.x *= rs * gg.x; v.y *= rs * gg.y; v.z *= rs * gg.z; v.w *= rs * gg.w;
;       *(float4*)(xr + i * 256 + lane * 4) = v;
.Lfin_sum_f:
	s_nop 1
	v_add_f32_dpp v42, v42, v42 quad_perm:[1,0,3,2] row_mask:0xf bank_mask:0xf
	s_nop 1
	v_add_f32_dpp v42, v42, v42 quad_perm:[2,3,0,1] row_mask:0xf bank_mask:0xf
	s_nop 1
	v_add_f32_dpp v42, v42, v42 row_half_mirror row_mask:0xf bank_mask:0xf
	s_nop 1
	v_add_f32_dpp v42, v42, v42 row_mirror row_mask:0xf bank_mask:0xf
	v_mov_b32_e32 v43, v42
	s_nop 1
	v_permlane16_swap_b32_e32 v43, v42
	v_add_f32_e32 v42, v42, v43
	v_mov_b32_e32 v43, v42
	s_nop 1
	v_permlane32_swap_b32_e32 v43, v42
	v_add_f32_e32 v42, v42, v43
	v_mov_b32_e32 v43, 0x358637bd
	v_fmamk_f32 v42, v42, 0x3a800000, v43
	v_rsq_f32_e32 v42, v42
	s_nop 0
	s_nop 1
	v_pk_mul_f32 v[44:45], v[16:17], v[42:43] op_sel_hi:[1,0]
	v_pk_mul_f32 v[0:1], v[0:1], v[44:45]
	v_pk_mul_f32 v[46:47], v[18:19], v[42:43] op_sel_hi:[1,0]
	v_pk_mul_f32 v[2:3], v[2:3], v[46:47]
	v_pk_mul_f32 v[44:45], v[20:21], v[42:43] op_sel_hi:[1,0]
	v_pk_mul_f32 v[4:5], v[4:5], v[44:45]
	v_pk_mul_f32 v[46:47], v[22:23], v[42:43] op_sel_hi:[1,0]
	v_pk_mul_f32 v[6:7], v[6:7], v[46:47]
	v_pk_mul_f32 v[44:45], v[24:25], v[42:43] op_sel_hi:[1,0]
	v_pk_mul_f32 v[8:9], v[8:9], v[44:45]
	v_pk_mul_f32 v[46:47], v[26:27], v[42:43] op_sel_hi:[1,0]
	v_pk_mul_f32 v[10:11], v[10:11], v[46:47]
	v_pk_mul_f32 v[44:45], v[28:29], v[42:43] op_sel_hi:[1,0]
	v_pk_mul_f32 v[12:13], v[12:13], v[44:45]
	v_pk_mul_f32 v[46:47], v[30:31], v[42:43] op_sel_hi:[1,0]
	v_pk_mul_f32 v[14:15], v[14:15], v[46:47]
	global_store_dwordx4 v40, v[0:3], s[8:9]
	global_store_dwordx4 v40, v[4:7], s[8:9] offset:1024
	global_store_dwordx4 v40, v[8:11], s[8:9] offset:2048
	global_store_dwordx4 v40, v[12:15], s[8:9] offset:3072

; __device__ __forceinline__ void final_phase(const Params& p) {
;     ...
;     s = wsum64(s);
;     const float rs = rsqrtf(s * (1.0f / 1024.0f) + 1e-6f);
;     float* xr = p.out + (size_t)row * 1024;
; #pragma unroll
;     for (int i = 0; i < 4; i++) {
;       float4 v = *(float4*)(xr + i * 256 + lane * 4);
;       float4 gg = *(const float4*)(g + i * 256 + lane * 4);
;       v.x *= rs * gg.x; v.y *= rs * gg.y; v.z *= rs * gg.z; v.w *= rs * gg.w;
;       *(float4*)(xr + i * 256 + lane * 4) = v;
;     }
.Lfin_sum_a:
	s_nop 1
	v_add_f32_dpp v42, v42, v42 quad_perm:[1,0,3,2] row_mask:0xf bank_mask:0xf
	s_nop 1
	v_add_f32_dpp v42, v42, v42 quad_perm:[2,3,0,1] row_mask:0xf bank_mask:0xf
	s_nop 1
	v_add_f32_dpp v42, v42, v42 row_half_mirror row_mask:0xf bank_mask:0xf
	s_nop 1
	v_add_f32_dpp v42, v42, v42 row_mirror row_mask:0xf bank_mask:0xf
	v_mov_b32_e32 v43, v42
	s_nop 1
	v_permlane16_swap_b32_e32 v43, v42
	v_add_f32_e32 v42, v42, v43
	v_mov_b32_e32 v43, v42
	s_nop 1
	v_permlane32_swap_b32_e32 v43, v42
	v_add_f32_e32 v42, v42, v43
	v_mov_b32_e32 v43, 0x358637bd
	v_fmamk_f32 v42, v42, 0x3a800000, v43
	v_rsq_f32_e32 v42, v42
	s_nop 0
	s_nop 1
	v_pk_mul_f32 v[44:45], v[16:17], v[42:43] op_sel_hi:[1,0]
	v_pk_mul_f32 v[48:49], v[48:49], v[44:45]
	v_pk_mul_f32 v[46:47], v[18:19], v[42:43] op_sel_hi:[1,0]
	v_pk_mul_f32 v[50:51], v[50:51], v[46:47]
	v_pk_mul_f32 v[44:45], v[20:21], v[42:43] op_sel_hi:[1,0]
	v_pk_mul_f32 v[52:53], v[52:53], v[44:45]
	v_pk_mul_f32 v[46:47], v[22:23], v[42:43] op_sel_hi:[1,0]
	v_pk_mul_f32 v[54:55], v[54:55], v[46:47]
	v_pk_mul_f32 v[44:45], v[24:25], v[42:43] op_sel_hi:[1,0]
	v_pk_mul_f32 v[56:57], v[56:57], v[44:45]
	v_pk_mul_f32 v[46:47], v[26:27], v[42:43] op_sel_hi:[1,0]
	v_pk_mul_f32 v[58:59], v[58:59], v[46:47]
	v_pk_mul_f32 v[44:45], v[28:29], v[42:43] op_sel_hi:[1,0]
	v_pk_mul_f32 v[60:61], v[60:61], v[44:45]
	v_pk_mul_f32 v[46:47], v[30:31], v[42:43] op_sel_hi:[1,0]
	v_pk_mul_f32 v[62:63], v[62:63], v[46:47]
	global_store_dwordx4 v40, v[48:51], s[10:11]
	global_store_dwordx4 v40, v[52:55], s[10:11] offset:1024
	global_store_dwordx4 v40, v[56:59], s[10:11] offset:2048
	global_store_dwordx4 v40, v[60:63], s[10:11] offset:3072
	s_cmp_eq_u32 s13, 1
	s_cbranch_scc1 .Lfin_done
	s_mov_b32 s13, 0
	s_add_u32 s2, s2, s12
	s_cmp_ge_u32 s2, 16896
	s_cbranch_scc1 .Lfin_nomore_b
	s_mov_b32 s15, s2
	s_lshl_b32 s4, s2, 12
	s_add_u32 s10, s94, s4
	s_addc_u32 s11, s95, 0
	s_lshl_b32 s4, s2, 6
	s_add_u32 s6, s96, s4
	s_addc_u32 s7, s97, 0
	global_load_dwordx4 v[48:51], v40, s[10:11]
	global_load_dwordx4 v[52:55], v40, s[10:11] offset:1024
	global_load_dwordx4 v[56:59], v40, s[10:11] offset:2048
	global_load_dwordx4 v[60:63], v40, s[10:11] offset:3072
	global_load_dword v80, v41, s[6:7]
	s_waitcnt vmcnt(9)
	s_branch .Lfin_go_b

; __device__ __forceinline__ void final_phase(const Params& p) {
;     ...
;     s = wsum64(s);
;     const float rs = rsqrtf(s * (1.0f / 1024.0f) + 1e-6f);
;     float* xr = p.out + (size_t)row * 1024;
; #pragma unroll
;     for (int i = 0; i < 4; i++) {
;       float4 v = *(float4*)(xr + i * 256 + lane * 4);
;       float4 gg = *(const float4*)(g + i * 256 + lane * 4);
;       v.x *= rs * gg.x; v.y *= rs * gg.y; v.z *= rs * gg.z; v.w *= rs * gg.w;
;       *(float4*)(xr + i * 256 + lane * 4) = v;
;     }
.Lfin_sum_b:
	s_nop 1
	v_add_f32_dpp v42, v42, v42 quad_perm:[1,0,3,2] row_mask:0xf bank_mask:0xf
	s_nop 1
	v_add_f32_dpp v42, v42, v42 quad_perm:[2,3,0,1] row_mask:0xf bank_mask:0xf
	s_nop 1
	v_add_f32_dpp v42, v42, v42 row_half_mirror row_mask:0xf bank_mask:0xf
	s_nop 1
	v_add_f32_dpp v42, v42, v42 row_mirror row_mask:0xf bank_mask:0xf
	v_mov_b32_e32 v43, v42
	s_nop 1
	v_permlane16_swap_b32_e32 v43, v42
	v_add_f32_e32 v42, v42, v43
	v_mov_b32_e32 v43, v42
	s_nop 1
	v_permlane32_swap_b32_e32 v43, v42
	v_add_f32_e32 v42, v42, v43
	v_mov_b32_e32 v43, 0x358637bd
	v_fmamk_f32 v42, v42, 0x3a800000, v43
	v_rsq_f32_e32 v42, v42
	s_nop 0
	s_nop 1
	v_pk_mul_f32 v[44:45], v[16:17], v[42:43] op_sel_hi:[1,0]
	v_pk_mul_f32 v[0:1], v[0:1], v[44:45]
	v_pk_mul_f32 v[46:47], v[18:19], v[42:43] op_sel_hi:[1,0]
	v_pk_mul_f32 v[2:3], v[2:3], v[46:47]
	v_pk_mul_f32 v[44:45], v[20:21], v[42:43] op_sel_hi:[1,0]
	v_pk_mul_f32 v[4:5], v[4:5], v[44:45]
	v_pk_mul_f32 v[46:47], v[22:23], v[42:43] op_sel_hi:[1,0]
	v_pk_mul_f32 v[6:7], v[6:7], v[46:47]
	v_pk_mul_f32 v[44:45], v[24:25], v[42:43] op_sel_hi:[1,0]
	v_pk_mul_f32 v[8:9], v[8:9], v[44:45]
	v_pk_mul_f32 v[46:47], v[26:27], v[42:43] op_sel_hi:[1,0]
	v_pk_mul_f32 v[10:11], v[10:11], v[46:47]
	v_pk_mul_f32 v[44:45], v[28:29], v[42:43] op_sel_hi:[1,0]
	v_pk_mul_f32 v[12:13], v[12:13], v[44:45]
	v_pk_mul_f32 v[46:47], v[30:31], v[42:43] op_sel_hi:[1,0]
	v_pk_mul_f32 v[14:15], v[14:15], v[46:47]
	global_store_dwordx4 v40, v[0:3], s[8:9]
	global_store_dwordx4 v40, v[4:7], s[8:9] offset:1024
	global_store_dwordx4 v40, v[8:11], s[8:9] offset:2048
	global_store_dwordx4 v40, v[12:15], s[8:9] offset:3072
	s_cmp_eq_u32 s13, 1
	s_cbranch_scc1 .Lfin_done
	s_branch .Lfin_loop
